# GEMM K-loops of P1,P3,P4,P5: LDS-DMA addressed by scalar base + 32-bit lane offset (SALU pointer math instead of per-load 64-bit VALU adds)
# speedup vs baseline: 1.0101x; 1.0036x over previous
.LBB0_126:
	ds_read_b128 v[130:133], v176
	ds_read_b128 v[134:137], v176 offset:1024
	ds_read_b128 v[170:173], v176 offset:2048
	ds_read_b128 v[180:183], v176 offset:3072
	ds_read_b128 v[184:187], v177
	ds_read_b128 v[188:191], v177 offset:1024
	ds_read_b128 v[192:195], v177 offset:2048
	ds_read_b128 v[198:201], v177 offset:3072
	s_add_u32 s14, s8, 0xfff00080
	s_addc_u32 s15, s9, -1
	s_cmp_eq_u32 s29, 60
	s_cselect_b32 s19, s11, s15
	s_cselect_b32 s18, s13, s14
	s_cselect_b32 s15, s17, s28
	s_cselect_b32 s14, s20, s21
	s_add_i32 m0, s73, 0xc000
	ds_read_b128 v[202:205], v178
	ds_read_b128 v[206:209], v178 offset:1024
	ds_read_b128 v[210:213], v178 offset:2048
	ds_read_b128 v[214:217], v178 offset:3072
	ds_read_b128 v[218:221], v178 offset:4096
	ds_read_b128 v[222:225], v178 offset:5120
	ds_read_b128 v[226:229], v178 offset:6144
	ds_read_b128 v[230:233], v178 offset:7168
	global_load_lds_dwordx4 v160, s[8:9]
	s_add_i32 m0, s73, 0xe000
	s_nop 0
	global_load_lds_dwordx4 v162, s[8:9]
	s_waitcnt vmcnt(8)
	s_waitcnt lgkmcnt(0)
	s_barrier
	s_setprio 1
	s_waitcnt lgkmcnt(0)
	v_mfma_f32_16x16x32_bf16 v[126:129], v[130:133], v[202:205], v[126:129]
	v_mfma_f32_16x16x32_bf16 v[122:125], v[170:173], v[202:205], v[122:125]
	v_mfma_f32_16x16x32_bf16 v[110:113], v[130:133], v[210:213], v[110:113]
	v_mfma_f32_16x16x32_bf16 v[106:109], v[170:173], v[210:213], v[106:109]
	v_mfma_f32_16x16x32_bf16 v[94:97], v[130:133], v[218:221], v[94:97]
	v_mfma_f32_16x16x32_bf16 v[90:93], v[170:173], v[218:221], v[90:93]
	v_mfma_f32_16x16x32_bf16 v[78:81], v[130:133], v[226:229], v[78:81]
	v_mfma_f32_16x16x32_bf16 v[74:77], v[170:173], v[226:229], v[74:77]
	v_mfma_f32_16x16x32_bf16 v[126:129], v[134:137], v[206:209], v[126:129]
	v_mfma_f32_16x16x32_bf16 v[122:125], v[180:183], v[206:209], v[122:125]
	v_mfma_f32_16x16x32_bf16 v[110:113], v[134:137], v[214:217], v[110:113]
	v_mfma_f32_16x16x32_bf16 v[106:109], v[180:183], v[214:217], v[106:109]
	v_mfma_f32_16x16x32_bf16 v[94:97], v[134:137], v[222:225], v[94:97]
	v_mfma_f32_16x16x32_bf16 v[90:93], v[180:183], v[222:225], v[90:93]
	v_mfma_f32_16x16x32_bf16 v[78:81], v[134:137], v[230:233], v[78:81]
	v_mfma_f32_16x16x32_bf16 v[74:77], v[180:183], v[230:233], v[74:77]
	s_setprio 0
	s_setprio 1
	v_mfma_f32_16x16x32_bf16 v[118:121], v[184:187], v[202:205], v[118:121]
	v_mfma_f32_16x16x32_bf16 v[114:117], v[192:195], v[202:205], v[114:117]
	v_mfma_f32_16x16x32_bf16 v[102:105], v[184:187], v[210:213], v[102:105]
	v_mfma_f32_16x16x32_bf16 v[98:101], v[192:195], v[210:213], v[98:101]
	v_mfma_f32_16x16x32_bf16 v[86:89], v[184:187], v[218:221], v[86:89]
	v_mfma_f32_16x16x32_bf16 v[82:85], v[192:195], v[218:221], v[82:85]
	v_mfma_f32_16x16x32_bf16 v[70:73], v[184:187], v[226:229], v[70:73]
	v_mfma_f32_16x16x32_bf16 v[66:69], v[192:195], v[226:229], v[66:69]
	v_mfma_f32_16x16x32_bf16 v[118:121], v[188:191], v[206:209], v[118:121]
	v_mfma_f32_16x16x32_bf16 v[114:117], v[198:201], v[206:209], v[114:117]
	v_mfma_f32_16x16x32_bf16 v[102:105], v[188:191], v[214:217], v[102:105]
	v_mfma_f32_16x16x32_bf16 v[98:101], v[198:201], v[214:217], v[98:101]
	v_mfma_f32_16x16x32_bf16 v[86:89], v[188:191], v[222:225], v[86:89]
	v_mfma_f32_16x16x32_bf16 v[82:85], v[198:201], v[222:225], v[82:85]
	v_mfma_f32_16x16x32_bf16 v[70:73], v[188:191], v[230:233], v[70:73]
	v_mfma_f32_16x16x32_bf16 v[66:69], v[198:201], v[230:233], v[66:69]
	s_setprio 0
	s_barrier
	s_add_i32 s30, s69, s35
	s_mov_b32 m0, s30
	ds_read_b128 v[202:205], v178 offset:16384
	ds_read_b128 v[206:209], v178 offset:17408
	ds_read_b128 v[210:213], v178 offset:18432
	ds_read_b128 v[214:217], v178 offset:19456
	ds_read_b128 v[218:221], v178 offset:20480
	ds_read_b128 v[222:225], v178 offset:21504
	ds_read_b128 v[226:229], v178 offset:22528
	ds_read_b128 v[230:233], v178 offset:23552
	global_load_lds_dwordx4 v140, s[14:15]
	s_add_i32 m0, s30, 0x2000
	s_add_u32 s30, s14, 0x100000
	s_addc_u32 s31, s15, 0
	s_add_i32 s38, s70, s35
	global_load_lds_dwordx4 v144, s[14:15]
	s_mov_b32 m0, s38
	global_load_lds_dwordx4 v140, s[30:31]
	s_add_i32 m0, s38, 0x2000
	s_nop 0
	global_load_lds_dwordx4 v144, s[30:31]
	s_mov_b32 m0, s73
	s_nop 0
	global_load_lds_dwordx4 v138, s[18:19]
	s_mov_b32 m0, s66
	s_nop 0
	global_load_lds_dwordx4 v142, s[18:19]
	s_waitcnt vmcnt(8)
	s_waitcnt lgkmcnt(0)
	s_barrier
	s_setprio 1
	s_waitcnt lgkmcnt(0)
	v_mfma_f32_16x16x32_bf16 v[62:65], v[130:133], v[202:205], v[62:65]
	v_mfma_f32_16x16x32_bf16 v[58:61], v[170:173], v[202:205], v[58:61]
	v_mfma_f32_16x16x32_bf16 v[46:49], v[130:133], v[210:213], v[46:49]
	v_mfma_f32_16x16x32_bf16 v[42:45], v[170:173], v[210:213], v[42:45]
	v_mfma_f32_16x16x32_bf16 v[30:33], v[130:133], v[218:221], v[30:33]
	v_mfma_f32_16x16x32_bf16 v[26:29], v[170:173], v[218:221], v[26:29]
	v_mfma_f32_16x16x32_bf16 v[14:17], v[130:133], v[226:229], v[14:17]
	v_mfma_f32_16x16x32_bf16 v[10:13], v[170:173], v[226:229], v[10:13]
	v_mfma_f32_16x16x32_bf16 v[62:65], v[134:137], v[206:209], v[62:65]
	v_mfma_f32_16x16x32_bf16 v[58:61], v[180:183], v[206:209], v[58:61]
	v_mfma_f32_16x16x32_bf16 v[46:49], v[134:137], v[214:217], v[46:49]
	v_mfma_f32_16x16x32_bf16 v[42:45], v[180:183], v[214:217], v[42:45]
	v_mfma_f32_16x16x32_bf16 v[30:33], v[134:137], v[222:225], v[30:33]
	v_mfma_f32_16x16x32_bf16 v[26:29], v[180:183], v[222:225], v[26:29]
	v_mfma_f32_16x16x32_bf16 v[14:17], v[134:137], v[230:233], v[14:17]
	v_mfma_f32_16x16x32_bf16 v[10:13], v[180:183], v[230:233], v[10:13]
	s_setprio 0
	s_setprio 1
	v_mfma_f32_16x16x32_bf16 v[54:57], v[184:187], v[202:205], v[54:57]
	v_mfma_f32_16x16x32_bf16 v[50:53], v[192:195], v[202:205], v[50:53]
	v_mfma_f32_16x16x32_bf16 v[38:41], v[184:187], v[210:213], v[38:41]
	v_mfma_f32_16x16x32_bf16 v[34:37], v[192:195], v[210:213], v[34:37]
	v_mfma_f32_16x16x32_bf16 v[22:25], v[184:187], v[218:221], v[22:25]
	v_mfma_f32_16x16x32_bf16 v[18:21], v[192:195], v[218:221], v[18:21]
	v_mfma_f32_16x16x32_bf16 v[6:9], v[184:187], v[226:229], v[6:9]
	v_mfma_f32_16x16x32_bf16 v[2:5], v[192:195], v[226:229], v[2:5]
	v_mfma_f32_16x16x32_bf16 v[54:57], v[188:191], v[206:209], v[54:57]
	v_mfma_f32_16x16x32_bf16 v[50:53], v[198:201], v[206:209], v[50:53]
	v_mfma_f32_16x16x32_bf16 v[38:41], v[188:191], v[214:217], v[38:41]
	v_mfma_f32_16x16x32_bf16 v[34:37], v[198:201], v[214:217], v[34:37]
	v_mfma_f32_16x16x32_bf16 v[22:25], v[188:191], v[222:225], v[22:25]
	v_mfma_f32_16x16x32_bf16 v[18:21], v[198:201], v[222:225], v[18:21]
	v_mfma_f32_16x16x32_bf16 v[6:9], v[188:191], v[230:233], v[6:9]
	v_mfma_f32_16x16x32_bf16 v[2:5], v[198:201], v[230:233], v[2:5]
	s_setprio 0
	s_barrier
	s_add_i32 s30, 0, 0x18000
	v_add_u32_e32 v146, s30, v155
	s_add_i32 s31, 0, 0x1c000
	ds_read_b128 v[130:133], v146
	ds_read_b128 v[134:137], v146 offset:1024
	ds_read_b128 v[170:173], v146 offset:2048
	ds_read_b128 v[180:183], v146 offset:3072
	v_add_u32_e32 v146, s31, v155
	ds_read_b128 v[184:187], v146
	ds_read_b128 v[188:191], v146 offset:1024
	ds_read_b128 v[192:195], v146 offset:2048
	ds_read_b128 v[198:201], v146 offset:3072
	s_add_u32 s18, s18, 0x100000
	s_addc_u32 s19, s19, 0
	s_mov_b32 m0, s67
	ds_read_b128 v[202:205], v178 offset:32768
	ds_read_b128 v[206:209], v178 offset:33792
	ds_read_b128 v[210:213], v178 offset:34816
	ds_read_b128 v[214:217], v178 offset:35840
	ds_read_b128 v[218:221], v178 offset:36864
	ds_read_b128 v[222:225], v178 offset:37888
	ds_read_b128 v[226:229], v178 offset:38912
	ds_read_b128 v[230:233], v178 offset:39936
	global_load_lds_dwordx4 v138, s[18:19]
	s_mov_b32 m0, s88
	s_nop 0
	global_load_lds_dwordx4 v142, s[18:19]
	s_waitcnt vmcnt(8)
	s_waitcnt lgkmcnt(0)
	s_barrier
	s_setprio 1
	s_waitcnt lgkmcnt(0)
	v_mfma_f32_16x16x32_bf16 v[126:129], v[130:133], v[202:205], v[126:129]
	v_mfma_f32_16x16x32_bf16 v[122:125], v[170:173], v[202:205], v[122:125]
	v_mfma_f32_16x16x32_bf16 v[110:113], v[130:133], v[210:213], v[110:113]
	v_mfma_f32_16x16x32_bf16 v[106:109], v[170:173], v[210:213], v[106:109]
	v_mfma_f32_16x16x32_bf16 v[94:97], v[130:133], v[218:221], v[94:97]
	v_mfma_f32_16x16x32_bf16 v[90:93], v[170:173], v[218:221], v[90:93]
	v_mfma_f32_16x16x32_bf16 v[78:81], v[130:133], v[226:229], v[78:81]
	v_mfma_f32_16x16x32_bf16 v[74:77], v[170:173], v[226:229], v[74:77]
	v_mfma_f32_16x16x32_bf16 v[126:129], v[134:137], v[206:209], v[126:129]
	v_mfma_f32_16x16x32_bf16 v[122:125], v[180:183], v[206:209], v[122:125]
	v_mfma_f32_16x16x32_bf16 v[110:113], v[134:137], v[214:217], v[110:113]
	v_mfma_f32_16x16x32_bf16 v[106:109], v[180:183], v[214:217], v[106:109]
	v_mfma_f32_16x16x32_bf16 v[94:97], v[134:137], v[222:225], v[94:97]
	v_mfma_f32_16x16x32_bf16 v[90:93], v[180:183], v[222:225], v[90:93]
	v_mfma_f32_16x16x32_bf16 v[78:81], v[134:137], v[230:233], v[78:81]
	v_mfma_f32_16x16x32_bf16 v[74:77], v[180:183], v[230:233], v[74:77]
	s_setprio 0
	s_setprio 1
	v_mfma_f32_16x16x32_bf16 v[118:121], v[184:187], v[202:205], v[118:121]
	v_mfma_f32_16x16x32_bf16 v[114:117], v[192:195], v[202:205], v[114:117]
	v_mfma_f32_16x16x32_bf16 v[102:105], v[184:187], v[210:213], v[102:105]
	v_mfma_f32_16x16x32_bf16 v[98:101], v[192:195], v[210:213], v[98:101]
	v_mfma_f32_16x16x32_bf16 v[86:89], v[184:187], v[218:221], v[86:89]
	v_mfma_f32_16x16x32_bf16 v[82:85], v[192:195], v[218:221], v[82:85]
	v_mfma_f32_16x16x32_bf16 v[70:73], v[184:187], v[226:229], v[70:73]
	v_mfma_f32_16x16x32_bf16 v[66:69], v[192:195], v[226:229], v[66:69]
	v_mfma_f32_16x16x32_bf16 v[118:121], v[188:191], v[206:209], v[118:121]
	v_mfma_f32_16x16x32_bf16 v[114:117], v[198:201], v[206:209], v[114:117]
	v_mfma_f32_16x16x32_bf16 v[102:105], v[188:191], v[214:217], v[102:105]
	v_mfma_f32_16x16x32_bf16 v[98:101], v[198:201], v[214:217], v[98:101]
	v_mfma_f32_16x16x32_bf16 v[86:89], v[188:191], v[222:225], v[86:89]
	v_mfma_f32_16x16x32_bf16 v[82:85], v[198:201], v[222:225], v[82:85]
	v_mfma_f32_16x16x32_bf16 v[70:73], v[188:191], v[230:233], v[70:73]
	v_mfma_f32_16x16x32_bf16 v[66:69], v[198:201], v[230:233], v[66:69]
	s_setprio 0
	s_barrier
	s_add_u32 s14, s14, 0x80
	s_addc_u32 s15, s15, 0
	s_add_i32 m0, s35, 0x18000
	ds_read_b128 v[202:205], v178 offset:49152
	ds_read_b128 v[206:209], v178 offset:50176
	ds_read_b128 v[210:213], v178 offset:51200
	ds_read_b128 v[214:217], v178 offset:52224
	ds_read_b128 v[218:221], v178 offset:53248
	ds_read_b128 v[222:225], v178 offset:54272
	ds_read_b128 v[226:229], v178 offset:55296
	ds_read_b128 v[230:233], v178 offset:56320
	global_load_lds_dwordx4 v140, s[14:15]
	s_add_i32 m0, s35, 0x1a000
	s_add_u32 s18, s18, 0xfff00080
	global_load_lds_dwordx4 v144, s[14:15]
	s_addc_u32 s19, s19, -1
	s_add_u32 s14, s14, 0x100000
	s_addc_u32 s15, s15, 0
	s_add_i32 m0, s35, 0x1c000
	s_nop 0
	global_load_lds_dwordx4 v140, s[14:15]
	s_add_i32 m0, s35, 0x1e000
	s_nop 0
	global_load_lds_dwordx4 v144, s[14:15]
	s_mov_b32 m0, s89
	s_nop 0
	global_load_lds_dwordx4 v138, s[18:19]
	s_mov_b32 m0, s68
	s_nop 0
	global_load_lds_dwordx4 v142, s[18:19]
	s_waitcnt vmcnt(8)
	s_waitcnt lgkmcnt(0)
	s_barrier
	s_setprio 1
	s_waitcnt lgkmcnt(0)
	v_mfma_f32_16x16x32_bf16 v[62:65], v[130:133], v[202:205], v[62:65]
	v_mfma_f32_16x16x32_bf16 v[58:61], v[170:173], v[202:205], v[58:61]
	v_mfma_f32_16x16x32_bf16 v[46:49], v[130:133], v[210:213], v[46:49]
	v_mfma_f32_16x16x32_bf16 v[42:45], v[170:173], v[210:213], v[42:45]
	v_mfma_f32_16x16x32_bf16 v[30:33], v[130:133], v[218:221], v[30:33]
	v_mfma_f32_16x16x32_bf16 v[26:29], v[170:173], v[218:221], v[26:29]
	v_mfma_f32_16x16x32_bf16 v[14:17], v[130:133], v[226:229], v[14:17]
	v_mfma_f32_16x16x32_bf16 v[10:13], v[170:173], v[226:229], v[10:13]
	v_mfma_f32_16x16x32_bf16 v[62:65], v[134:137], v[206:209], v[62:65]
	v_mfma_f32_16x16x32_bf16 v[58:61], v[180:183], v[206:209], v[58:61]
	v_mfma_f32_16x16x32_bf16 v[46:49], v[134:137], v[214:217], v[46:49]
	v_mfma_f32_16x16x32_bf16 v[42:45], v[180:183], v[214:217], v[42:45]
	v_mfma_f32_16x16x32_bf16 v[30:33], v[134:137], v[222:225], v[30:33]
	v_mfma_f32_16x16x32_bf16 v[26:29], v[180:183], v[222:225], v[26:29]
	v_mfma_f32_16x16x32_bf16 v[14:17], v[134:137], v[230:233], v[14:17]
	v_mfma_f32_16x16x32_bf16 v[10:13], v[180:183], v[230:233], v[10:13]
	s_setprio 0
	s_setprio 1
	v_mfma_f32_16x16x32_bf16 v[54:57], v[184:187], v[202:205], v[54:57]
	v_mfma_f32_16x16x32_bf16 v[50:53], v[192:195], v[202:205], v[50:53]
	v_mfma_f32_16x16x32_bf16 v[38:41], v[184:187], v[210:213], v[38:41]
	v_mfma_f32_16x16x32_bf16 v[34:37], v[192:195], v[210:213], v[34:37]
	v_mfma_f32_16x16x32_bf16 v[22:25], v[184:187], v[218:221], v[22:25]
	v_mfma_f32_16x16x32_bf16 v[18:21], v[192:195], v[218:221], v[18:21]
	v_mfma_f32_16x16x32_bf16 v[6:9], v[184:187], v[226:229], v[6:9]
	v_mfma_f32_16x16x32_bf16 v[2:5], v[192:195], v[226:229], v[2:5]
	v_mfma_f32_16x16x32_bf16 v[54:57], v[188:191], v[206:209], v[54:57]
	v_mfma_f32_16x16x32_bf16 v[50:53], v[198:201], v[206:209], v[50:53]
	v_mfma_f32_16x16x32_bf16 v[38:41], v[188:191], v[214:217], v[38:41]
	v_mfma_f32_16x16x32_bf16 v[34:37], v[198:201], v[214:217], v[34:37]
	v_mfma_f32_16x16x32_bf16 v[22:25], v[188:191], v[222:225], v[22:25]
	v_mfma_f32_16x16x32_bf16 v[18:21], v[198:201], v[222:225], v[18:21]
	v_mfma_f32_16x16x32_bf16 v[6:9], v[188:191], v[230:233], v[6:9]
	v_mfma_f32_16x16x32_bf16 v[2:5], v[198:201], v[230:233], v[2:5]
	s_setprio 0
	s_barrier
	s_add_i32 s29, s29, 2
	s_add_u32 s8, s8, 0x100
	s_addc_u32 s9, s9, 0
	s_add_u32 s21, s21, 0x100
	s_addc_u32 s28, s28, 0
	s_cmp_gt_u32 s29, 61
	s_cbranch_scc0 .LBB0_126
	v_readlane_b32 s8, v249, 56
	v_readlane_b32 s9, v249, 57
	s_and_b64 vcc, exec, s[8:9]
	s_cbranch_vccz .LBB0_129
	s_barrier

.LBB0_678:
	ds_read_b128 v[148:151], v159
	ds_read_b128 v[152:155], v159 offset:1024
	ds_read_b128 v[164:167], v159 offset:2048
	ds_read_b128 v[168:171], v159 offset:3072
	ds_read_b128 v[172:175], v160
	ds_read_b128 v[176:179], v160 offset:1024
	ds_read_b128 v[180:183], v160 offset:2048
	ds_read_b128 v[184:187], v160 offset:3072
	s_add_u32 s60, s58, 0xfff00080
	s_addc_u32 s61, s59, -1
	s_cmp_eq_u32 s78, 60
	s_cselect_b32 s63, s7, s61
	s_cselect_b32 s62, s47, s60
	s_cselect_b32 s61, s45, s77
	s_cselect_b32 s60, s57, s76
	s_add_i32 m0, s64, 0xc000
	ds_read_b128 v[188:191], v161
	ds_read_b128 v[192:195], v161 offset:1024
	ds_read_b128 v[198:201], v161 offset:2048
	ds_read_b128 v[202:205], v161 offset:3072
	ds_read_b128 v[206:209], v161 offset:4096
	ds_read_b128 v[210:213], v161 offset:5120
	ds_read_b128 v[214:217], v161 offset:6144
	ds_read_b128 v[218:221], v161 offset:7168
	global_load_lds_dwordx4 v140, s[58:59]
	s_add_i32 m0, s64, 0xe000
	s_nop 0
	global_load_lds_dwordx4 v142, s[58:59]
	s_waitcnt vmcnt(8)
	s_waitcnt lgkmcnt(0)
	s_barrier
	s_setprio 1
	s_waitcnt lgkmcnt(0)
	v_mfma_f32_16x16x32_bf16 v[126:129], v[148:151], v[188:191], v[126:129]
	v_mfma_f32_16x16x32_bf16 v[122:125], v[164:167], v[188:191], v[122:125]
	v_mfma_f32_16x16x32_bf16 v[110:113], v[148:151], v[198:201], v[110:113]
	v_mfma_f32_16x16x32_bf16 v[106:109], v[164:167], v[198:201], v[106:109]
	v_mfma_f32_16x16x32_bf16 v[94:97], v[148:151], v[206:209], v[94:97]
	v_mfma_f32_16x16x32_bf16 v[90:93], v[164:167], v[206:209], v[90:93]
	v_mfma_f32_16x16x32_bf16 v[78:81], v[148:151], v[214:217], v[78:81]
	v_mfma_f32_16x16x32_bf16 v[74:77], v[164:167], v[214:217], v[74:77]
	v_mfma_f32_16x16x32_bf16 v[126:129], v[152:155], v[192:195], v[126:129]
	v_mfma_f32_16x16x32_bf16 v[122:125], v[168:171], v[192:195], v[122:125]
	v_mfma_f32_16x16x32_bf16 v[110:113], v[152:155], v[202:205], v[110:113]
	v_mfma_f32_16x16x32_bf16 v[106:109], v[168:171], v[202:205], v[106:109]
	v_mfma_f32_16x16x32_bf16 v[94:97], v[152:155], v[210:213], v[94:97]
	v_mfma_f32_16x16x32_bf16 v[90:93], v[168:171], v[210:213], v[90:93]
	v_mfma_f32_16x16x32_bf16 v[78:81], v[152:155], v[218:221], v[78:81]
	v_mfma_f32_16x16x32_bf16 v[74:77], v[168:171], v[218:221], v[74:77]
	s_setprio 0
	s_setprio 1
	v_mfma_f32_16x16x32_bf16 v[118:121], v[172:175], v[188:191], v[118:121]
	v_mfma_f32_16x16x32_bf16 v[114:117], v[180:183], v[188:191], v[114:117]
	v_mfma_f32_16x16x32_bf16 v[102:105], v[172:175], v[198:201], v[102:105]
	v_mfma_f32_16x16x32_bf16 v[98:101], v[180:183], v[198:201], v[98:101]
	v_mfma_f32_16x16x32_bf16 v[86:89], v[172:175], v[206:209], v[86:89]
	v_mfma_f32_16x16x32_bf16 v[82:85], v[180:183], v[206:209], v[82:85]
	v_mfma_f32_16x16x32_bf16 v[70:73], v[172:175], v[214:217], v[70:73]
	v_mfma_f32_16x16x32_bf16 v[66:69], v[180:183], v[214:217], v[66:69]
	v_mfma_f32_16x16x32_bf16 v[118:121], v[176:179], v[192:195], v[118:121]
	v_mfma_f32_16x16x32_bf16 v[114:117], v[184:187], v[192:195], v[114:117]
	v_mfma_f32_16x16x32_bf16 v[102:105], v[176:179], v[202:205], v[102:105]
	v_mfma_f32_16x16x32_bf16 v[98:101], v[184:187], v[202:205], v[98:101]
	v_mfma_f32_16x16x32_bf16 v[86:89], v[176:179], v[210:213], v[86:89]
	v_mfma_f32_16x16x32_bf16 v[82:85], v[184:187], v[210:213], v[82:85]
	v_mfma_f32_16x16x32_bf16 v[70:73], v[176:179], v[218:221], v[70:73]
	v_mfma_f32_16x16x32_bf16 v[66:69], v[184:187], v[218:221], v[66:69]
	s_setprio 0
	s_barrier
	s_add_i32 s79, s74, s33
	s_mov_b32 m0, s79
	ds_read_b128 v[188:191], v161 offset:16384
	ds_read_b128 v[192:195], v161 offset:17408
	ds_read_b128 v[198:201], v161 offset:18432
	ds_read_b128 v[202:205], v161 offset:19456
	ds_read_b128 v[206:209], v161 offset:20480
	ds_read_b128 v[210:213], v161 offset:21504
	ds_read_b128 v[214:217], v161 offset:22528
	ds_read_b128 v[218:221], v161 offset:23552
	global_load_lds_dwordx4 v132, s[60:61]
	s_add_i32 m0, s79, 0x2000
	s_add_u32 s80, s60, 0x100000
	s_addc_u32 s81, s61, 0
	s_add_i32 s79, s75, s33
	global_load_lds_dwordx4 v136, s[60:61]
	s_mov_b32 m0, s79
	global_load_lds_dwordx4 v132, s[80:81]
	s_add_i32 m0, s79, 0x2000
	s_nop 0
	global_load_lds_dwordx4 v136, s[80:81]
	s_mov_b32 m0, s64
	s_nop 0
	global_load_lds_dwordx4 v130, s[62:63]
	s_mov_b32 m0, s65
	s_nop 0
	global_load_lds_dwordx4 v134, s[62:63]
	s_waitcnt vmcnt(8)
	s_waitcnt lgkmcnt(0)
	s_barrier
	s_setprio 1
	s_waitcnt lgkmcnt(0)
	v_mfma_f32_16x16x32_bf16 v[62:65], v[148:151], v[188:191], v[62:65]
	v_mfma_f32_16x16x32_bf16 v[58:61], v[164:167], v[188:191], v[58:61]
	v_mfma_f32_16x16x32_bf16 v[46:49], v[148:151], v[198:201], v[46:49]
	v_mfma_f32_16x16x32_bf16 v[42:45], v[164:167], v[198:201], v[42:45]
	v_mfma_f32_16x16x32_bf16 v[30:33], v[148:151], v[206:209], v[30:33]
	v_mfma_f32_16x16x32_bf16 v[26:29], v[164:167], v[206:209], v[26:29]
	v_mfma_f32_16x16x32_bf16 v[14:17], v[148:151], v[214:217], v[14:17]
	v_mfma_f32_16x16x32_bf16 v[10:13], v[164:167], v[214:217], v[10:13]
	v_mfma_f32_16x16x32_bf16 v[62:65], v[152:155], v[192:195], v[62:65]
	v_mfma_f32_16x16x32_bf16 v[58:61], v[168:171], v[192:195], v[58:61]
	v_mfma_f32_16x16x32_bf16 v[46:49], v[152:155], v[202:205], v[46:49]
	v_mfma_f32_16x16x32_bf16 v[42:45], v[168:171], v[202:205], v[42:45]
	v_mfma_f32_16x16x32_bf16 v[30:33], v[152:155], v[210:213], v[30:33]
	v_mfma_f32_16x16x32_bf16 v[26:29], v[168:171], v[210:213], v[26:29]
	v_mfma_f32_16x16x32_bf16 v[14:17], v[152:155], v[218:221], v[14:17]
	v_mfma_f32_16x16x32_bf16 v[10:13], v[168:171], v[218:221], v[10:13]
	s_setprio 0
	s_setprio 1
	v_mfma_f32_16x16x32_bf16 v[54:57], v[172:175], v[188:191], v[54:57]
	v_mfma_f32_16x16x32_bf16 v[50:53], v[180:183], v[188:191], v[50:53]
	v_mfma_f32_16x16x32_bf16 v[38:41], v[172:175], v[198:201], v[38:41]
	v_mfma_f32_16x16x32_bf16 v[34:37], v[180:183], v[198:201], v[34:37]
	v_mfma_f32_16x16x32_bf16 v[22:25], v[172:175], v[206:209], v[22:25]
	v_mfma_f32_16x16x32_bf16 v[18:21], v[180:183], v[206:209], v[18:21]
	v_mfma_f32_16x16x32_bf16 v[6:9], v[172:175], v[214:217], v[6:9]
	v_mfma_f32_16x16x32_bf16 v[2:5], v[180:183], v[214:217], v[2:5]
	v_mfma_f32_16x16x32_bf16 v[54:57], v[176:179], v[192:195], v[54:57]
	v_mfma_f32_16x16x32_bf16 v[50:53], v[184:187], v[192:195], v[50:53]
	v_mfma_f32_16x16x32_bf16 v[38:41], v[176:179], v[202:205], v[38:41]
	v_mfma_f32_16x16x32_bf16 v[34:37], v[184:187], v[202:205], v[34:37]
	v_mfma_f32_16x16x32_bf16 v[22:25], v[176:179], v[210:213], v[22:25]
	v_mfma_f32_16x16x32_bf16 v[18:21], v[184:187], v[210:213], v[18:21]
	v_mfma_f32_16x16x32_bf16 v[6:9], v[176:179], v[218:221], v[6:9]
	v_mfma_f32_16x16x32_bf16 v[2:5], v[184:187], v[218:221], v[2:5]
	s_setprio 0
	s_barrier
	s_add_i32 s79, 0, 0x18000
	v_add_u32_e32 v138, s79, v157
	s_add_i32 s80, 0, 0x1c000
	ds_read_b128 v[148:151], v138
	ds_read_b128 v[152:155], v138 offset:1024
	ds_read_b128 v[164:167], v138 offset:2048
	ds_read_b128 v[168:171], v138 offset:3072
	v_add_u32_e32 v138, s80, v157
	ds_read_b128 v[172:175], v138
	ds_read_b128 v[176:179], v138 offset:1024
	ds_read_b128 v[180:183], v138 offset:2048
	ds_read_b128 v[184:187], v138 offset:3072
	s_add_u32 s62, s62, 0x100000
	s_addc_u32 s63, s63, 0
	s_mov_b32 m0, s66
	ds_read_b128 v[188:191], v161 offset:32768
	ds_read_b128 v[192:195], v161 offset:33792
	ds_read_b128 v[198:201], v161 offset:34816
	ds_read_b128 v[202:205], v161 offset:35840
	ds_read_b128 v[206:209], v161 offset:36864
	ds_read_b128 v[210:213], v161 offset:37888
	ds_read_b128 v[214:217], v161 offset:38912
	ds_read_b128 v[218:221], v161 offset:39936
	global_load_lds_dwordx4 v130, s[62:63]
	s_mov_b32 m0, s67
	s_nop 0
	global_load_lds_dwordx4 v134, s[62:63]
	s_waitcnt vmcnt(8)
	s_waitcnt lgkmcnt(0)
	s_barrier
	s_setprio 1
	s_waitcnt lgkmcnt(0)
	v_mfma_f32_16x16x32_bf16 v[126:129], v[148:151], v[188:191], v[126:129]
	v_mfma_f32_16x16x32_bf16 v[122:125], v[164:167], v[188:191], v[122:125]
	v_mfma_f32_16x16x32_bf16 v[110:113], v[148:151], v[198:201], v[110:113]
	v_mfma_f32_16x16x32_bf16 v[106:109], v[164:167], v[198:201], v[106:109]
	v_mfma_f32_16x16x32_bf16 v[94:97], v[148:151], v[206:209], v[94:97]
	v_mfma_f32_16x16x32_bf16 v[90:93], v[164:167], v[206:209], v[90:93]
	v_mfma_f32_16x16x32_bf16 v[78:81], v[148:151], v[214:217], v[78:81]
	v_mfma_f32_16x16x32_bf16 v[74:77], v[164:167], v[214:217], v[74:77]
	v_mfma_f32_16x16x32_bf16 v[126:129], v[152:155], v[192:195], v[126:129]
	v_mfma_f32_16x16x32_bf16 v[122:125], v[168:171], v[192:195], v[122:125]
	v_mfma_f32_16x16x32_bf16 v[110:113], v[152:155], v[202:205], v[110:113]
	v_mfma_f32_16x16x32_bf16 v[106:109], v[168:171], v[202:205], v[106:109]
	v_mfma_f32_16x16x32_bf16 v[94:97], v[152:155], v[210:213], v[94:97]
	v_mfma_f32_16x16x32_bf16 v[90:93], v[168:171], v[210:213], v[90:93]
	v_mfma_f32_16x16x32_bf16 v[78:81], v[152:155], v[218:221], v[78:81]
	v_mfma_f32_16x16x32_bf16 v[74:77], v[168:171], v[218:221], v[74:77]
	s_setprio 0
	s_setprio 1
	v_mfma_f32_16x16x32_bf16 v[118:121], v[172:175], v[188:191], v[118:121]
	v_mfma_f32_16x16x32_bf16 v[114:117], v[180:183], v[188:191], v[114:117]
	v_mfma_f32_16x16x32_bf16 v[102:105], v[172:175], v[198:201], v[102:105]
	v_mfma_f32_16x16x32_bf16 v[98:101], v[180:183], v[198:201], v[98:101]
	v_mfma_f32_16x16x32_bf16 v[86:89], v[172:175], v[206:209], v[86:89]
	v_mfma_f32_16x16x32_bf16 v[82:85], v[180:183], v[206:209], v[82:85]
	v_mfma_f32_16x16x32_bf16 v[70:73], v[172:175], v[214:217], v[70:73]
	v_mfma_f32_16x16x32_bf16 v[66:69], v[180:183], v[214:217], v[66:69]
	v_mfma_f32_16x16x32_bf16 v[118:121], v[176:179], v[192:195], v[118:121]
	v_mfma_f32_16x16x32_bf16 v[114:117], v[184:187], v[192:195], v[114:117]
	v_mfma_f32_16x16x32_bf16 v[102:105], v[176:179], v[202:205], v[102:105]
	v_mfma_f32_16x16x32_bf16 v[98:101], v[184:187], v[202:205], v[98:101]
	v_mfma_f32_16x16x32_bf16 v[86:89], v[176:179], v[210:213], v[86:89]
	v_mfma_f32_16x16x32_bf16 v[82:85], v[184:187], v[210:213], v[82:85]
	v_mfma_f32_16x16x32_bf16 v[70:73], v[176:179], v[218:221], v[70:73]
	v_mfma_f32_16x16x32_bf16 v[66:69], v[184:187], v[218:221], v[66:69]
	s_setprio 0
	s_barrier
	s_add_u32 s60, s60, 0x80
	s_addc_u32 s61, s61, 0
	s_add_i32 m0, s33, 0x18000
	ds_read_b128 v[188:191], v161 offset:49152
	ds_read_b128 v[192:195], v161 offset:50176
	ds_read_b128 v[198:201], v161 offset:51200
	ds_read_b128 v[202:205], v161 offset:52224
	ds_read_b128 v[206:209], v161 offset:53248
	ds_read_b128 v[210:213], v161 offset:54272
	ds_read_b128 v[214:217], v161 offset:55296
	ds_read_b128 v[218:221], v161 offset:56320
	global_load_lds_dwordx4 v132, s[60:61]
	s_add_i32 m0, s33, 0x1a000
	s_add_u32 s62, s62, 0xfff00080
	global_load_lds_dwordx4 v136, s[60:61]
	s_addc_u32 s63, s63, -1
	s_add_u32 s60, s60, 0x100000
	s_addc_u32 s61, s61, 0
	s_add_i32 m0, s33, 0x1c000
	s_nop 0
	global_load_lds_dwordx4 v132, s[60:61]
	s_add_i32 m0, s33, 0x1e000
	s_nop 0
	global_load_lds_dwordx4 v136, s[60:61]
	s_mov_b32 m0, s69
	s_nop 0
	global_load_lds_dwordx4 v130, s[62:63]
	s_mov_b32 m0, s70
	s_nop 0
	global_load_lds_dwordx4 v134, s[62:63]
	s_waitcnt vmcnt(8)
	s_waitcnt lgkmcnt(0)
	s_barrier
	s_setprio 1
	s_waitcnt lgkmcnt(0)
	v_mfma_f32_16x16x32_bf16 v[62:65], v[148:151], v[188:191], v[62:65]
	v_mfma_f32_16x16x32_bf16 v[58:61], v[164:167], v[188:191], v[58:61]
	v_mfma_f32_16x16x32_bf16 v[46:49], v[148:151], v[198:201], v[46:49]
	v_mfma_f32_16x16x32_bf16 v[42:45], v[164:167], v[198:201], v[42:45]
	v_mfma_f32_16x16x32_bf16 v[30:33], v[148:151], v[206:209], v[30:33]
	v_mfma_f32_16x16x32_bf16 v[26:29], v[164:167], v[206:209], v[26:29]
	v_mfma_f32_16x16x32_bf16 v[14:17], v[148:151], v[214:217], v[14:17]
	v_mfma_f32_16x16x32_bf16 v[10:13], v[164:167], v[214:217], v[10:13]
	v_mfma_f32_16x16x32_bf16 v[62:65], v[152:155], v[192:195], v[62:65]
	v_mfma_f32_16x16x32_bf16 v[58:61], v[168:171], v[192:195], v[58:61]
	v_mfma_f32_16x16x32_bf16 v[46:49], v[152:155], v[202:205], v[46:49]
	v_mfma_f32_16x16x32_bf16 v[42:45], v[168:171], v[202:205], v[42:45]
	v_mfma_f32_16x16x32_bf16 v[30:33], v[152:155], v[210:213], v[30:33]
	v_mfma_f32_16x16x32_bf16 v[26:29], v[168:171], v[210:213], v[26:29]
	v_mfma_f32_16x16x32_bf16 v[14:17], v[152:155], v[218:221], v[14:17]
	v_mfma_f32_16x16x32_bf16 v[10:13], v[168:171], v[218:221], v[10:13]
	s_setprio 0
	s_setprio 1
	v_mfma_f32_16x16x32_bf16 v[54:57], v[172:175], v[188:191], v[54:57]
	v_mfma_f32_16x16x32_bf16 v[50:53], v[180:183], v[188:191], v[50:53]
	v_mfma_f32_16x16x32_bf16 v[38:41], v[172:175], v[198:201], v[38:41]
	v_mfma_f32_16x16x32_bf16 v[34:37], v[180:183], v[198:201], v[34:37]
	v_mfma_f32_16x16x32_bf16 v[22:25], v[172:175], v[206:209], v[22:25]
	v_mfma_f32_16x16x32_bf16 v[18:21], v[180:183], v[206:209], v[18:21]
	v_mfma_f32_16x16x32_bf16 v[6:9], v[172:175], v[214:217], v[6:9]
	v_mfma_f32_16x16x32_bf16 v[2:5], v[180:183], v[214:217], v[2:5]
	v_mfma_f32_16x16x32_bf16 v[54:57], v[176:179], v[192:195], v[54:57]
	v_mfma_f32_16x16x32_bf16 v[50:53], v[184:187], v[192:195], v[50:53]
	v_mfma_f32_16x16x32_bf16 v[38:41], v[176:179], v[202:205], v[38:41]
	v_mfma_f32_16x16x32_bf16 v[34:37], v[184:187], v[202:205], v[34:37]
	v_mfma_f32_16x16x32_bf16 v[22:25], v[176:179], v[210:213], v[22:25]
	v_mfma_f32_16x16x32_bf16 v[18:21], v[184:187], v[210:213], v[18:21]
	v_mfma_f32_16x16x32_bf16 v[6:9], v[176:179], v[218:221], v[6:9]
	v_mfma_f32_16x16x32_bf16 v[2:5], v[184:187], v[218:221], v[2:5]
	s_setprio 0
	s_barrier
	s_add_i32 s78, s78, 2
	s_add_u32 s58, s58, 0x100
	s_addc_u32 s59, s59, 0
	s_add_u32 s76, s76, 0x100
	s_addc_u32 s77, s77, 0
	s_cmp_gt_u32 s78, 61
	s_cbranch_scc0 .LBB0_678
	s_and_b64 vcc, exec, s[18:19]
	s_cbranch_vccz .LBB0_681
	s_barrier

.LBB0_807:
	ds_read_b128 v[154:157], v150
	ds_read_b128 v[158:161], v150 offset:1024
	ds_read_b128 v[162:165], v150 offset:2048
	ds_read_b128 v[166:169], v150 offset:3072
	ds_read_b128 v[170:173], v151
	ds_read_b128 v[174:177], v151 offset:1024
	ds_read_b128 v[178:181], v151 offset:2048
	ds_read_b128 v[182:185], v151 offset:3072
	s_add_u32 s44, s42, 0xfff00080
	s_addc_u32 s45, s43, -1
	s_cmp_eq_u32 s68, 60
	s_cselect_b32 s47, s35, s45
	s_cselect_b32 s46, s64, s44
	s_cselect_b32 s45, s31, s67
	s_cselect_b32 s44, s65, s66
	s_add_i32 m0, s41, 0xc000
	ds_read_b128 v[186:189], v152
	ds_read_b128 v[190:193], v152 offset:1024
	ds_read_b128 v[198:201], v152 offset:2048
	ds_read_b128 v[202:205], v152 offset:3072
	ds_read_b128 v[206:209], v152 offset:4096
	ds_read_b128 v[210:213], v152 offset:5120
	ds_read_b128 v[214:217], v152 offset:6144
	ds_read_b128 v[218:221], v152 offset:7168
	global_load_lds_dwordx4 v138, s[42:43]
	s_add_i32 m0, s41, 0xe000
	s_nop 0
	global_load_lds_dwordx4 v140, s[42:43]
	s_waitcnt vmcnt(8)
	s_waitcnt lgkmcnt(0)
	s_barrier
	s_setprio 1
	s_waitcnt lgkmcnt(0)
	v_mfma_f32_16x16x32_bf16 v[126:129], v[154:157], v[186:189], v[126:129]
	v_mfma_f32_16x16x32_bf16 v[122:125], v[162:165], v[186:189], v[122:125]
	v_mfma_f32_16x16x32_bf16 v[110:113], v[154:157], v[198:201], v[110:113]
	v_mfma_f32_16x16x32_bf16 v[106:109], v[162:165], v[198:201], v[106:109]
	v_mfma_f32_16x16x32_bf16 v[94:97], v[154:157], v[206:209], v[94:97]
	v_mfma_f32_16x16x32_bf16 v[90:93], v[162:165], v[206:209], v[90:93]
	v_mfma_f32_16x16x32_bf16 v[78:81], v[154:157], v[214:217], v[78:81]
	v_mfma_f32_16x16x32_bf16 v[74:77], v[162:165], v[214:217], v[74:77]
	v_mfma_f32_16x16x32_bf16 v[126:129], v[158:161], v[190:193], v[126:129]
	v_mfma_f32_16x16x32_bf16 v[122:125], v[166:169], v[190:193], v[122:125]
	v_mfma_f32_16x16x32_bf16 v[110:113], v[158:161], v[202:205], v[110:113]
	v_mfma_f32_16x16x32_bf16 v[106:109], v[166:169], v[202:205], v[106:109]
	v_mfma_f32_16x16x32_bf16 v[94:97], v[158:161], v[210:213], v[94:97]
	v_mfma_f32_16x16x32_bf16 v[90:93], v[166:169], v[210:213], v[90:93]
	v_mfma_f32_16x16x32_bf16 v[78:81], v[158:161], v[218:221], v[78:81]
	v_mfma_f32_16x16x32_bf16 v[74:77], v[166:169], v[218:221], v[74:77]
	s_setprio 0
	s_setprio 1
	v_mfma_f32_16x16x32_bf16 v[118:121], v[170:173], v[186:189], v[118:121]
	v_mfma_f32_16x16x32_bf16 v[114:117], v[178:181], v[186:189], v[114:117]
	v_mfma_f32_16x16x32_bf16 v[102:105], v[170:173], v[198:201], v[102:105]
	v_mfma_f32_16x16x32_bf16 v[98:101], v[178:181], v[198:201], v[98:101]
	v_mfma_f32_16x16x32_bf16 v[86:89], v[170:173], v[206:209], v[86:89]
	v_mfma_f32_16x16x32_bf16 v[82:85], v[178:181], v[206:209], v[82:85]
	v_mfma_f32_16x16x32_bf16 v[70:73], v[170:173], v[214:217], v[70:73]
	v_mfma_f32_16x16x32_bf16 v[66:69], v[178:181], v[214:217], v[66:69]
	v_mfma_f32_16x16x32_bf16 v[118:121], v[174:177], v[190:193], v[118:121]
	v_mfma_f32_16x16x32_bf16 v[114:117], v[182:185], v[190:193], v[114:117]
	v_mfma_f32_16x16x32_bf16 v[102:105], v[174:177], v[202:205], v[102:105]
	v_mfma_f32_16x16x32_bf16 v[98:101], v[182:185], v[202:205], v[98:101]
	v_mfma_f32_16x16x32_bf16 v[86:89], v[174:177], v[210:213], v[86:89]
	v_mfma_f32_16x16x32_bf16 v[82:85], v[182:185], v[210:213], v[82:85]
	v_mfma_f32_16x16x32_bf16 v[70:73], v[174:177], v[218:221], v[70:73]
	v_mfma_f32_16x16x32_bf16 v[66:69], v[182:185], v[218:221], v[66:69]
	s_setprio 0
	s_barrier
	s_add_i32 s69, s57, s33
	s_mov_b32 m0, s69
	ds_read_b128 v[186:189], v152 offset:16384
	ds_read_b128 v[190:193], v152 offset:17408
	ds_read_b128 v[198:201], v152 offset:18432
	ds_read_b128 v[202:205], v152 offset:19456
	ds_read_b128 v[206:209], v152 offset:20480
	ds_read_b128 v[210:213], v152 offset:21504
	ds_read_b128 v[214:217], v152 offset:22528
	ds_read_b128 v[218:221], v152 offset:23552
	global_load_lds_dwordx4 v132, s[44:45]
	s_add_i32 m0, s69, 0x2000
	s_add_u32 s70, s44, 0x100000
	s_addc_u32 s71, s45, 0
	s_add_i32 s69, s58, s33
	global_load_lds_dwordx4 v136, s[44:45]
	s_mov_b32 m0, s69
	global_load_lds_dwordx4 v132, s[70:71]
	s_add_i32 m0, s69, 0x2000
	s_nop 0
	global_load_lds_dwordx4 v136, s[70:71]
	s_mov_b32 m0, s41
	s_nop 0
	global_load_lds_dwordx4 v130, s[46:47]
	s_mov_b32 m0, s50
	s_nop 0
	global_load_lds_dwordx4 v134, s[46:47]
	s_waitcnt vmcnt(8)
	s_waitcnt lgkmcnt(0)
	s_barrier
	s_setprio 1
	s_waitcnt lgkmcnt(0)
	v_mfma_f32_16x16x32_bf16 v[62:65], v[154:157], v[186:189], v[62:65]
	v_mfma_f32_16x16x32_bf16 v[58:61], v[162:165], v[186:189], v[58:61]
	v_mfma_f32_16x16x32_bf16 v[46:49], v[154:157], v[198:201], v[46:49]
	v_mfma_f32_16x16x32_bf16 v[42:45], v[162:165], v[198:201], v[42:45]
	v_mfma_f32_16x16x32_bf16 v[30:33], v[154:157], v[206:209], v[30:33]
	v_mfma_f32_16x16x32_bf16 v[26:29], v[162:165], v[206:209], v[26:29]
	v_mfma_f32_16x16x32_bf16 v[14:17], v[154:157], v[214:217], v[14:17]
	v_mfma_f32_16x16x32_bf16 v[10:13], v[162:165], v[214:217], v[10:13]
	v_mfma_f32_16x16x32_bf16 v[62:65], v[158:161], v[190:193], v[62:65]
	v_mfma_f32_16x16x32_bf16 v[58:61], v[166:169], v[190:193], v[58:61]
	v_mfma_f32_16x16x32_bf16 v[46:49], v[158:161], v[202:205], v[46:49]
	v_mfma_f32_16x16x32_bf16 v[42:45], v[166:169], v[202:205], v[42:45]
	v_mfma_f32_16x16x32_bf16 v[30:33], v[158:161], v[210:213], v[30:33]
	v_mfma_f32_16x16x32_bf16 v[26:29], v[166:169], v[210:213], v[26:29]
	v_mfma_f32_16x16x32_bf16 v[14:17], v[158:161], v[218:221], v[14:17]
	v_mfma_f32_16x16x32_bf16 v[10:13], v[166:169], v[218:221], v[10:13]
	s_setprio 0
	s_setprio 1
	v_mfma_f32_16x16x32_bf16 v[54:57], v[170:173], v[186:189], v[54:57]
	v_mfma_f32_16x16x32_bf16 v[50:53], v[178:181], v[186:189], v[50:53]
	v_mfma_f32_16x16x32_bf16 v[38:41], v[170:173], v[198:201], v[38:41]
	v_mfma_f32_16x16x32_bf16 v[34:37], v[178:181], v[198:201], v[34:37]
	v_mfma_f32_16x16x32_bf16 v[22:25], v[170:173], v[206:209], v[22:25]
	v_mfma_f32_16x16x32_bf16 v[18:21], v[178:181], v[206:209], v[18:21]
	v_mfma_f32_16x16x32_bf16 v[6:9], v[170:173], v[214:217], v[6:9]
	v_mfma_f32_16x16x32_bf16 v[2:5], v[178:181], v[214:217], v[2:5]
	v_mfma_f32_16x16x32_bf16 v[54:57], v[174:177], v[190:193], v[54:57]
	v_mfma_f32_16x16x32_bf16 v[50:53], v[182:185], v[190:193], v[50:53]
	v_mfma_f32_16x16x32_bf16 v[38:41], v[174:177], v[202:205], v[38:41]
	v_mfma_f32_16x16x32_bf16 v[34:37], v[182:185], v[202:205], v[34:37]
	v_mfma_f32_16x16x32_bf16 v[22:25], v[174:177], v[210:213], v[22:25]
	v_mfma_f32_16x16x32_bf16 v[18:21], v[182:185], v[210:213], v[18:21]
	v_mfma_f32_16x16x32_bf16 v[6:9], v[174:177], v[218:221], v[6:9]
	v_mfma_f32_16x16x32_bf16 v[2:5], v[182:185], v[218:221], v[2:5]
	s_setprio 0
	s_barrier
	s_add_i32 s69, 0, 0x18000
	v_add_u32_e32 v153, s69, v148
	s_add_i32 s70, 0, 0x1c000
	ds_read_b128 v[154:157], v153
	ds_read_b128 v[158:161], v153 offset:1024
	ds_read_b128 v[162:165], v153 offset:2048
	ds_read_b128 v[166:169], v153 offset:3072
	v_add_u32_e32 v153, s70, v148
	ds_read_b128 v[170:173], v153
	ds_read_b128 v[174:177], v153 offset:1024
	ds_read_b128 v[178:181], v153 offset:2048
	ds_read_b128 v[182:185], v153 offset:3072
	s_add_u32 s46, s46, 0x100000
	s_addc_u32 s47, s47, 0
	s_mov_b32 m0, s51
	ds_read_b128 v[186:189], v152 offset:32768
	ds_read_b128 v[190:193], v152 offset:33792
	ds_read_b128 v[198:201], v152 offset:34816
	ds_read_b128 v[202:205], v152 offset:35840
	ds_read_b128 v[206:209], v152 offset:36864
	ds_read_b128 v[210:213], v152 offset:37888
	ds_read_b128 v[214:217], v152 offset:38912
	ds_read_b128 v[218:221], v152 offset:39936
	global_load_lds_dwordx4 v130, s[46:47]
	s_mov_b32 m0, s52
	s_nop 0
	global_load_lds_dwordx4 v134, s[46:47]
	s_waitcnt vmcnt(8)
	s_waitcnt lgkmcnt(0)
	s_barrier
	s_setprio 1
	s_waitcnt lgkmcnt(0)
	v_mfma_f32_16x16x32_bf16 v[126:129], v[154:157], v[186:189], v[126:129]
	v_mfma_f32_16x16x32_bf16 v[122:125], v[162:165], v[186:189], v[122:125]
	v_mfma_f32_16x16x32_bf16 v[110:113], v[154:157], v[198:201], v[110:113]
	v_mfma_f32_16x16x32_bf16 v[106:109], v[162:165], v[198:201], v[106:109]
	v_mfma_f32_16x16x32_bf16 v[94:97], v[154:157], v[206:209], v[94:97]
	v_mfma_f32_16x16x32_bf16 v[90:93], v[162:165], v[206:209], v[90:93]
	v_mfma_f32_16x16x32_bf16 v[78:81], v[154:157], v[214:217], v[78:81]
	v_mfma_f32_16x16x32_bf16 v[74:77], v[162:165], v[214:217], v[74:77]
	v_mfma_f32_16x16x32_bf16 v[126:129], v[158:161], v[190:193], v[126:129]
	v_mfma_f32_16x16x32_bf16 v[122:125], v[166:169], v[190:193], v[122:125]
	v_mfma_f32_16x16x32_bf16 v[110:113], v[158:161], v[202:205], v[110:113]
	v_mfma_f32_16x16x32_bf16 v[106:109], v[166:169], v[202:205], v[106:109]
	v_mfma_f32_16x16x32_bf16 v[94:97], v[158:161], v[210:213], v[94:97]
	v_mfma_f32_16x16x32_bf16 v[90:93], v[166:169], v[210:213], v[90:93]
	v_mfma_f32_16x16x32_bf16 v[78:81], v[158:161], v[218:221], v[78:81]
	v_mfma_f32_16x16x32_bf16 v[74:77], v[166:169], v[218:221], v[74:77]
	s_setprio 0
	s_setprio 1
	v_mfma_f32_16x16x32_bf16 v[118:121], v[170:173], v[186:189], v[118:121]
	v_mfma_f32_16x16x32_bf16 v[114:117], v[178:181], v[186:189], v[114:117]
	v_mfma_f32_16x16x32_bf16 v[102:105], v[170:173], v[198:201], v[102:105]
	v_mfma_f32_16x16x32_bf16 v[98:101], v[178:181], v[198:201], v[98:101]
	v_mfma_f32_16x16x32_bf16 v[86:89], v[170:173], v[206:209], v[86:89]
	v_mfma_f32_16x16x32_bf16 v[82:85], v[178:181], v[206:209], v[82:85]
	v_mfma_f32_16x16x32_bf16 v[70:73], v[170:173], v[214:217], v[70:73]
	v_mfma_f32_16x16x32_bf16 v[66:69], v[178:181], v[214:217], v[66:69]
	v_mfma_f32_16x16x32_bf16 v[118:121], v[174:177], v[190:193], v[118:121]
	v_mfma_f32_16x16x32_bf16 v[114:117], v[182:185], v[190:193], v[114:117]
	v_mfma_f32_16x16x32_bf16 v[102:105], v[174:177], v[202:205], v[102:105]
	v_mfma_f32_16x16x32_bf16 v[98:101], v[182:185], v[202:205], v[98:101]
	v_mfma_f32_16x16x32_bf16 v[86:89], v[174:177], v[210:213], v[86:89]
	v_mfma_f32_16x16x32_bf16 v[82:85], v[182:185], v[210:213], v[82:85]
	v_mfma_f32_16x16x32_bf16 v[70:73], v[174:177], v[218:221], v[70:73]
	v_mfma_f32_16x16x32_bf16 v[66:69], v[182:185], v[218:221], v[66:69]
	s_setprio 0
	s_barrier
	s_add_u32 s44, s44, 0x80
	s_addc_u32 s45, s45, 0
	s_add_i32 m0, s33, 0x18000
	ds_read_b128 v[186:189], v152 offset:49152
	ds_read_b128 v[190:193], v152 offset:50176
	ds_read_b128 v[198:201], v152 offset:51200
	ds_read_b128 v[202:205], v152 offset:52224
	ds_read_b128 v[206:209], v152 offset:53248
	ds_read_b128 v[210:213], v152 offset:54272
	ds_read_b128 v[214:217], v152 offset:55296
	ds_read_b128 v[218:221], v152 offset:56320
	global_load_lds_dwordx4 v132, s[44:45]
	s_add_i32 m0, s33, 0x1a000
	s_add_u32 s46, s46, 0xfff00080
	global_load_lds_dwordx4 v136, s[44:45]
	s_addc_u32 s47, s47, -1
	s_add_u32 s44, s44, 0x100000
	s_addc_u32 s45, s45, 0
	s_add_i32 m0, s33, 0x1c000
	s_nop 0
	global_load_lds_dwordx4 v132, s[44:45]
	s_add_i32 m0, s33, 0x1e000
	s_nop 0
	global_load_lds_dwordx4 v136, s[44:45]
	s_mov_b32 m0, s55
	s_nop 0
	global_load_lds_dwordx4 v130, s[46:47]
	s_mov_b32 m0, s56
	s_nop 0
	global_load_lds_dwordx4 v134, s[46:47]
	s_waitcnt vmcnt(8)
	s_waitcnt lgkmcnt(0)
	s_barrier
	s_setprio 1
	s_waitcnt lgkmcnt(0)
	v_mfma_f32_16x16x32_bf16 v[62:65], v[154:157], v[186:189], v[62:65]
	v_mfma_f32_16x16x32_bf16 v[58:61], v[162:165], v[186:189], v[58:61]
	v_mfma_f32_16x16x32_bf16 v[46:49], v[154:157], v[198:201], v[46:49]
	v_mfma_f32_16x16x32_bf16 v[42:45], v[162:165], v[198:201], v[42:45]
	v_mfma_f32_16x16x32_bf16 v[30:33], v[154:157], v[206:209], v[30:33]
	v_mfma_f32_16x16x32_bf16 v[26:29], v[162:165], v[206:209], v[26:29]
	v_mfma_f32_16x16x32_bf16 v[14:17], v[154:157], v[214:217], v[14:17]
	v_mfma_f32_16x16x32_bf16 v[10:13], v[162:165], v[214:217], v[10:13]
	v_mfma_f32_16x16x32_bf16 v[62:65], v[158:161], v[190:193], v[62:65]
	v_mfma_f32_16x16x32_bf16 v[58:61], v[166:169], v[190:193], v[58:61]
	v_mfma_f32_16x16x32_bf16 v[46:49], v[158:161], v[202:205], v[46:49]
	v_mfma_f32_16x16x32_bf16 v[42:45], v[166:169], v[202:205], v[42:45]
	v_mfma_f32_16x16x32_bf16 v[30:33], v[158:161], v[210:213], v[30:33]
	v_mfma_f32_16x16x32_bf16 v[26:29], v[166:169], v[210:213], v[26:29]
	v_mfma_f32_16x16x32_bf16 v[14:17], v[158:161], v[218:221], v[14:17]
	v_mfma_f32_16x16x32_bf16 v[10:13], v[166:169], v[218:221], v[10:13]
	s_setprio 0
	s_setprio 1
	v_mfma_f32_16x16x32_bf16 v[54:57], v[170:173], v[186:189], v[54:57]
	v_mfma_f32_16x16x32_bf16 v[50:53], v[178:181], v[186:189], v[50:53]
	v_mfma_f32_16x16x32_bf16 v[38:41], v[170:173], v[198:201], v[38:41]
	v_mfma_f32_16x16x32_bf16 v[34:37], v[178:181], v[198:201], v[34:37]
	v_mfma_f32_16x16x32_bf16 v[22:25], v[170:173], v[206:209], v[22:25]
	v_mfma_f32_16x16x32_bf16 v[18:21], v[178:181], v[206:209], v[18:21]
	v_mfma_f32_16x16x32_bf16 v[6:9], v[170:173], v[214:217], v[6:9]
	v_mfma_f32_16x16x32_bf16 v[2:5], v[178:181], v[214:217], v[2:5]
	v_mfma_f32_16x16x32_bf16 v[54:57], v[174:177], v[190:193], v[54:57]
	v_mfma_f32_16x16x32_bf16 v[50:53], v[182:185], v[190:193], v[50:53]
	v_mfma_f32_16x16x32_bf16 v[38:41], v[174:177], v[202:205], v[38:41]
	v_mfma_f32_16x16x32_bf16 v[34:37], v[182:185], v[202:205], v[34:37]
	v_mfma_f32_16x16x32_bf16 v[22:25], v[174:177], v[210:213], v[22:25]
	v_mfma_f32_16x16x32_bf16 v[18:21], v[182:185], v[210:213], v[18:21]
	v_mfma_f32_16x16x32_bf16 v[6:9], v[174:177], v[218:221], v[6:9]
	v_mfma_f32_16x16x32_bf16 v[2:5], v[182:185], v[218:221], v[2:5]
	s_setprio 0
	s_barrier
	s_add_i32 s68, s68, 2
	s_add_u32 s42, s42, 0x100
	s_addc_u32 s43, s43, 0
	s_add_u32 s66, s66, 0x100
	s_addc_u32 s67, s67, 0
	s_cmp_gt_u32 s68, 61
	s_cbranch_scc0 .LBB0_807
	s_and_b64 vcc, exec, s[14:15]
	s_cbranch_vccz .LBB0_810
	s_barrier

.LBB0_897:
	ds_read_b128 v[146:149], v156
	ds_read_b128 v[150:153], v156 offset:1024
	ds_read_b128 v[160:163], v156 offset:2048
	ds_read_b128 v[164:167], v156 offset:3072
	ds_read_b128 v[168:171], v157
	ds_read_b128 v[172:175], v157 offset:1024
	ds_read_b128 v[176:179], v157 offset:2048
	ds_read_b128 v[180:183], v157 offset:3072
	s_add_u32 s44, s42, 0xffc00080
	s_addc_u32 s45, s43, -1
	s_cmpk_eq_i32 s67, 0xfc
	s_cselect_b32 s47, s35, s45
	s_cselect_b32 s46, s63, s44
	s_cselect_b32 s45, s31, s66
	s_cselect_b32 s44, s64, s65
	s_add_i32 m0, s41, 0xc000
	ds_read_b128 v[184:187], v158
	ds_read_b128 v[188:191], v158 offset:1024
	ds_read_b128 v[192:195], v158 offset:2048
	ds_read_b128 v[198:201], v158 offset:3072
	ds_read_b128 v[202:205], v158 offset:4096
	ds_read_b128 v[206:209], v158 offset:5120
	ds_read_b128 v[210:213], v158 offset:6144
	ds_read_b128 v[214:217], v158 offset:7168
	global_load_lds_dwordx4 v138, s[42:43]
	s_add_i32 m0, s41, 0xe000
	s_nop 0
	global_load_lds_dwordx4 v140, s[42:43]
	s_waitcnt vmcnt(8)
	s_waitcnt lgkmcnt(0)
	s_barrier
	s_setprio 1
	s_waitcnt lgkmcnt(0)
	v_mfma_f32_16x16x32_bf16 v[126:129], v[146:149], v[184:187], v[126:129]
	v_mfma_f32_16x16x32_bf16 v[122:125], v[160:163], v[184:187], v[122:125]
	v_mfma_f32_16x16x32_bf16 v[110:113], v[146:149], v[192:195], v[110:113]
	v_mfma_f32_16x16x32_bf16 v[106:109], v[160:163], v[192:195], v[106:109]
	v_mfma_f32_16x16x32_bf16 v[94:97], v[146:149], v[202:205], v[94:97]
	v_mfma_f32_16x16x32_bf16 v[90:93], v[160:163], v[202:205], v[90:93]
	v_mfma_f32_16x16x32_bf16 v[78:81], v[146:149], v[210:213], v[78:81]
	v_mfma_f32_16x16x32_bf16 v[74:77], v[160:163], v[210:213], v[74:77]
	v_mfma_f32_16x16x32_bf16 v[126:129], v[150:153], v[188:191], v[126:129]
	v_mfma_f32_16x16x32_bf16 v[122:125], v[164:167], v[188:191], v[122:125]
	v_mfma_f32_16x16x32_bf16 v[110:113], v[150:153], v[198:201], v[110:113]
	v_mfma_f32_16x16x32_bf16 v[106:109], v[164:167], v[198:201], v[106:109]
	v_mfma_f32_16x16x32_bf16 v[94:97], v[150:153], v[206:209], v[94:97]
	v_mfma_f32_16x16x32_bf16 v[90:93], v[164:167], v[206:209], v[90:93]
	v_mfma_f32_16x16x32_bf16 v[78:81], v[150:153], v[214:217], v[78:81]
	v_mfma_f32_16x16x32_bf16 v[74:77], v[164:167], v[214:217], v[74:77]
	s_setprio 0
	s_setprio 1
	v_mfma_f32_16x16x32_bf16 v[118:121], v[168:171], v[184:187], v[118:121]
	v_mfma_f32_16x16x32_bf16 v[114:117], v[176:179], v[184:187], v[114:117]
	v_mfma_f32_16x16x32_bf16 v[102:105], v[168:171], v[192:195], v[102:105]
	v_mfma_f32_16x16x32_bf16 v[98:101], v[176:179], v[192:195], v[98:101]
	v_mfma_f32_16x16x32_bf16 v[86:89], v[168:171], v[202:205], v[86:89]
	v_mfma_f32_16x16x32_bf16 v[82:85], v[176:179], v[202:205], v[82:85]
	v_mfma_f32_16x16x32_bf16 v[70:73], v[168:171], v[210:213], v[70:73]
	v_mfma_f32_16x16x32_bf16 v[66:69], v[176:179], v[210:213], v[66:69]
	v_mfma_f32_16x16x32_bf16 v[118:121], v[172:175], v[188:191], v[118:121]
	v_mfma_f32_16x16x32_bf16 v[114:117], v[180:183], v[188:191], v[114:117]
	v_mfma_f32_16x16x32_bf16 v[102:105], v[172:175], v[198:201], v[102:105]
	v_mfma_f32_16x16x32_bf16 v[98:101], v[180:183], v[198:201], v[98:101]
	v_mfma_f32_16x16x32_bf16 v[86:89], v[172:175], v[206:209], v[86:89]
	v_mfma_f32_16x16x32_bf16 v[82:85], v[180:183], v[206:209], v[82:85]
	v_mfma_f32_16x16x32_bf16 v[70:73], v[172:175], v[214:217], v[70:73]
	v_mfma_f32_16x16x32_bf16 v[66:69], v[180:183], v[214:217], v[66:69]
	s_setprio 0
	s_barrier
	s_add_i32 s68, s56, s48
	s_mov_b32 m0, s68
	ds_read_b128 v[184:187], v158 offset:16384
	ds_read_b128 v[188:191], v158 offset:17408
	ds_read_b128 v[192:195], v158 offset:18432
	ds_read_b128 v[198:201], v158 offset:19456
	ds_read_b128 v[202:205], v158 offset:20480
	ds_read_b128 v[206:209], v158 offset:21504
	ds_read_b128 v[210:213], v158 offset:22528
	ds_read_b128 v[214:217], v158 offset:23552
	global_load_lds_dwordx4 v132, s[44:45]
	s_add_i32 m0, s68, 0x2000
	s_add_u32 s68, s44, 0x400000
	s_addc_u32 s69, s45, 0
	s_add_i32 s70, s57, s48
	global_load_lds_dwordx4 v136, s[44:45]
	s_mov_b32 m0, s70
	global_load_lds_dwordx4 v132, s[68:69]
	s_add_i32 m0, s70, 0x2000
	s_nop 0
	global_load_lds_dwordx4 v136, s[68:69]
	s_mov_b32 m0, s41
	s_nop 0
	global_load_lds_dwordx4 v130, s[46:47]
	s_mov_b32 m0, s49
	s_nop 0
	global_load_lds_dwordx4 v134, s[46:47]
	s_waitcnt vmcnt(8)
	s_waitcnt lgkmcnt(0)
	s_barrier
	s_setprio 1
	s_waitcnt lgkmcnt(0)
	v_mfma_f32_16x16x32_bf16 v[62:65], v[146:149], v[184:187], v[62:65]
	v_mfma_f32_16x16x32_bf16 v[58:61], v[160:163], v[184:187], v[58:61]
	v_mfma_f32_16x16x32_bf16 v[46:49], v[146:149], v[192:195], v[46:49]
	v_mfma_f32_16x16x32_bf16 v[42:45], v[160:163], v[192:195], v[42:45]
	v_mfma_f32_16x16x32_bf16 v[30:33], v[146:149], v[202:205], v[30:33]
	v_mfma_f32_16x16x32_bf16 v[26:29], v[160:163], v[202:205], v[26:29]
	v_mfma_f32_16x16x32_bf16 v[14:17], v[146:149], v[210:213], v[14:17]
	v_mfma_f32_16x16x32_bf16 v[10:13], v[160:163], v[210:213], v[10:13]
	v_mfma_f32_16x16x32_bf16 v[62:65], v[150:153], v[188:191], v[62:65]
	v_mfma_f32_16x16x32_bf16 v[58:61], v[164:167], v[188:191], v[58:61]
	v_mfma_f32_16x16x32_bf16 v[46:49], v[150:153], v[198:201], v[46:49]
	v_mfma_f32_16x16x32_bf16 v[42:45], v[164:167], v[198:201], v[42:45]
	v_mfma_f32_16x16x32_bf16 v[30:33], v[150:153], v[206:209], v[30:33]
	v_mfma_f32_16x16x32_bf16 v[26:29], v[164:167], v[206:209], v[26:29]
	v_mfma_f32_16x16x32_bf16 v[14:17], v[150:153], v[214:217], v[14:17]
	v_mfma_f32_16x16x32_bf16 v[10:13], v[164:167], v[214:217], v[10:13]
	s_setprio 0
	s_setprio 1
	v_mfma_f32_16x16x32_bf16 v[54:57], v[168:171], v[184:187], v[54:57]
	v_mfma_f32_16x16x32_bf16 v[50:53], v[176:179], v[184:187], v[50:53]
	v_mfma_f32_16x16x32_bf16 v[38:41], v[168:171], v[192:195], v[38:41]
	v_mfma_f32_16x16x32_bf16 v[34:37], v[176:179], v[192:195], v[34:37]
	v_mfma_f32_16x16x32_bf16 v[22:25], v[168:171], v[202:205], v[22:25]
	v_mfma_f32_16x16x32_bf16 v[18:21], v[176:179], v[202:205], v[18:21]
	v_mfma_f32_16x16x32_bf16 v[6:9], v[168:171], v[210:213], v[6:9]
	v_mfma_f32_16x16x32_bf16 v[2:5], v[176:179], v[210:213], v[2:5]
	v_mfma_f32_16x16x32_bf16 v[54:57], v[172:175], v[188:191], v[54:57]
	v_mfma_f32_16x16x32_bf16 v[50:53], v[180:183], v[188:191], v[50:53]
	v_mfma_f32_16x16x32_bf16 v[38:41], v[172:175], v[198:201], v[38:41]
	v_mfma_f32_16x16x32_bf16 v[34:37], v[180:183], v[198:201], v[34:37]
	v_mfma_f32_16x16x32_bf16 v[22:25], v[172:175], v[206:209], v[22:25]
	v_mfma_f32_16x16x32_bf16 v[18:21], v[180:183], v[206:209], v[18:21]
	v_mfma_f32_16x16x32_bf16 v[6:9], v[172:175], v[214:217], v[6:9]
	v_mfma_f32_16x16x32_bf16 v[2:5], v[180:183], v[214:217], v[2:5]
	s_setprio 0
	s_barrier
	s_add_i32 s68, 0, 0x18000
	s_add_i32 s69, 0, 0x1c000
	v_add_u32_e32 v164, s68, v154
	v_add_u32_e32 v180, s69, v154
	ds_read_b128 v[146:149], v164
	ds_read_b128 v[150:153], v164 offset:1024
	ds_read_b128 v[160:163], v164 offset:2048
	ds_read_b128 v[164:167], v164 offset:3072
	ds_read_b128 v[168:171], v180
	ds_read_b128 v[172:175], v180 offset:1024
	ds_read_b128 v[176:179], v180 offset:2048
	ds_read_b128 v[180:183], v180 offset:3072
	s_add_u32 s46, s46, 0x400000
	s_addc_u32 s47, s47, 0
	s_mov_b32 m0, s50
	ds_read_b128 v[184:187], v158 offset:32768
	ds_read_b128 v[188:191], v158 offset:33792
	ds_read_b128 v[192:195], v158 offset:34816
	ds_read_b128 v[198:201], v158 offset:35840
	ds_read_b128 v[202:205], v158 offset:36864
	ds_read_b128 v[206:209], v158 offset:37888
	ds_read_b128 v[210:213], v158 offset:38912
	ds_read_b128 v[214:217], v158 offset:39936
	global_load_lds_dwordx4 v130, s[46:47]
	s_mov_b32 m0, s51
	s_nop 0
	global_load_lds_dwordx4 v134, s[46:47]
	s_waitcnt vmcnt(8)
	s_waitcnt lgkmcnt(0)
	s_barrier
	s_setprio 1
	s_waitcnt lgkmcnt(0)
	v_mfma_f32_16x16x32_bf16 v[126:129], v[146:149], v[184:187], v[126:129]
	v_mfma_f32_16x16x32_bf16 v[122:125], v[160:163], v[184:187], v[122:125]
	v_mfma_f32_16x16x32_bf16 v[110:113], v[146:149], v[192:195], v[110:113]
	v_mfma_f32_16x16x32_bf16 v[106:109], v[160:163], v[192:195], v[106:109]
	v_mfma_f32_16x16x32_bf16 v[94:97], v[146:149], v[202:205], v[94:97]
	v_mfma_f32_16x16x32_bf16 v[90:93], v[160:163], v[202:205], v[90:93]
	v_mfma_f32_16x16x32_bf16 v[78:81], v[146:149], v[210:213], v[78:81]
	v_mfma_f32_16x16x32_bf16 v[74:77], v[160:163], v[210:213], v[74:77]
	v_mfma_f32_16x16x32_bf16 v[126:129], v[150:153], v[188:191], v[126:129]
	v_mfma_f32_16x16x32_bf16 v[122:125], v[164:167], v[188:191], v[122:125]
	v_mfma_f32_16x16x32_bf16 v[110:113], v[150:153], v[198:201], v[110:113]
	v_mfma_f32_16x16x32_bf16 v[106:109], v[164:167], v[198:201], v[106:109]
	v_mfma_f32_16x16x32_bf16 v[94:97], v[150:153], v[206:209], v[94:97]
	v_mfma_f32_16x16x32_bf16 v[90:93], v[164:167], v[206:209], v[90:93]
	v_mfma_f32_16x16x32_bf16 v[78:81], v[150:153], v[214:217], v[78:81]
	v_mfma_f32_16x16x32_bf16 v[74:77], v[164:167], v[214:217], v[74:77]
	s_setprio 0
	s_setprio 1
	v_mfma_f32_16x16x32_bf16 v[118:121], v[168:171], v[184:187], v[118:121]
	v_mfma_f32_16x16x32_bf16 v[114:117], v[176:179], v[184:187], v[114:117]
	v_mfma_f32_16x16x32_bf16 v[102:105], v[168:171], v[192:195], v[102:105]
	v_mfma_f32_16x16x32_bf16 v[98:101], v[176:179], v[192:195], v[98:101]
	v_mfma_f32_16x16x32_bf16 v[86:89], v[168:171], v[202:205], v[86:89]
	v_mfma_f32_16x16x32_bf16 v[82:85], v[176:179], v[202:205], v[82:85]
	v_mfma_f32_16x16x32_bf16 v[70:73], v[168:171], v[210:213], v[70:73]
	v_mfma_f32_16x16x32_bf16 v[66:69], v[176:179], v[210:213], v[66:69]
	v_mfma_f32_16x16x32_bf16 v[118:121], v[172:175], v[188:191], v[118:121]
	v_mfma_f32_16x16x32_bf16 v[114:117], v[180:183], v[188:191], v[114:117]
	v_mfma_f32_16x16x32_bf16 v[102:105], v[172:175], v[198:201], v[102:105]
	v_mfma_f32_16x16x32_bf16 v[98:101], v[180:183], v[198:201], v[98:101]
	v_mfma_f32_16x16x32_bf16 v[86:89], v[172:175], v[206:209], v[86:89]
	v_mfma_f32_16x16x32_bf16 v[82:85], v[180:183], v[206:209], v[82:85]
	v_mfma_f32_16x16x32_bf16 v[70:73], v[172:175], v[214:217], v[70:73]
	v_mfma_f32_16x16x32_bf16 v[66:69], v[180:183], v[214:217], v[66:69]
	s_setprio 0
	s_barrier
	s_add_u32 s44, s44, 0x80
	s_addc_u32 s45, s45, 0
	s_add_i32 m0, s48, 0x18000
	ds_read_b128 v[184:187], v158 offset:49152
	ds_read_b128 v[188:191], v158 offset:50176
	ds_read_b128 v[192:195], v158 offset:51200
	ds_read_b128 v[198:201], v158 offset:52224
	ds_read_b128 v[202:205], v158 offset:53248
	ds_read_b128 v[206:209], v158 offset:54272
	ds_read_b128 v[210:213], v158 offset:55296
	ds_read_b128 v[214:217], v158 offset:56320
	global_load_lds_dwordx4 v132, s[44:45]
	s_add_i32 m0, s48, 0x1a000
	s_add_u32 s46, s46, 0xffc00080
	global_load_lds_dwordx4 v136, s[44:45]
	s_addc_u32 s47, s47, -1
	s_add_u32 s44, s44, 0x400000
	s_addc_u32 s45, s45, 0
	s_add_i32 m0, s48, 0x1c000
	s_nop 0
	global_load_lds_dwordx4 v132, s[44:45]
	s_add_i32 m0, s48, 0x1e000
	s_nop 0
	global_load_lds_dwordx4 v136, s[44:45]
	s_mov_b32 m0, s53
	s_nop 0
	global_load_lds_dwordx4 v130, s[46:47]
	s_mov_b32 m0, s54
	s_nop 0
	global_load_lds_dwordx4 v134, s[46:47]
	s_waitcnt vmcnt(8)
	s_waitcnt lgkmcnt(0)
	s_barrier
	s_setprio 1
	s_waitcnt lgkmcnt(0)
	v_mfma_f32_16x16x32_bf16 v[62:65], v[146:149], v[184:187], v[62:65]
	v_mfma_f32_16x16x32_bf16 v[58:61], v[160:163], v[184:187], v[58:61]
	v_mfma_f32_16x16x32_bf16 v[46:49], v[146:149], v[192:195], v[46:49]
	v_mfma_f32_16x16x32_bf16 v[42:45], v[160:163], v[192:195], v[42:45]
	v_mfma_f32_16x16x32_bf16 v[30:33], v[146:149], v[202:205], v[30:33]
	v_mfma_f32_16x16x32_bf16 v[26:29], v[160:163], v[202:205], v[26:29]
	v_mfma_f32_16x16x32_bf16 v[14:17], v[146:149], v[210:213], v[14:17]
	v_mfma_f32_16x16x32_bf16 v[10:13], v[160:163], v[210:213], v[10:13]
	v_mfma_f32_16x16x32_bf16 v[62:65], v[150:153], v[188:191], v[62:65]
	v_mfma_f32_16x16x32_bf16 v[58:61], v[164:167], v[188:191], v[58:61]
	v_mfma_f32_16x16x32_bf16 v[46:49], v[150:153], v[198:201], v[46:49]
	v_mfma_f32_16x16x32_bf16 v[42:45], v[164:167], v[198:201], v[42:45]
	v_mfma_f32_16x16x32_bf16 v[30:33], v[150:153], v[206:209], v[30:33]
	v_mfma_f32_16x16x32_bf16 v[26:29], v[164:167], v[206:209], v[26:29]
	v_mfma_f32_16x16x32_bf16 v[14:17], v[150:153], v[214:217], v[14:17]
	v_mfma_f32_16x16x32_bf16 v[10:13], v[164:167], v[214:217], v[10:13]
	s_setprio 0
	s_setprio 1
	v_mfma_f32_16x16x32_bf16 v[54:57], v[168:171], v[184:187], v[54:57]
	v_mfma_f32_16x16x32_bf16 v[50:53], v[176:179], v[184:187], v[50:53]
	v_mfma_f32_16x16x32_bf16 v[38:41], v[168:171], v[192:195], v[38:41]
	v_mfma_f32_16x16x32_bf16 v[34:37], v[176:179], v[192:195], v[34:37]
	v_mfma_f32_16x16x32_bf16 v[22:25], v[168:171], v[202:205], v[22:25]
	v_mfma_f32_16x16x32_bf16 v[18:21], v[176:179], v[202:205], v[18:21]
	v_mfma_f32_16x16x32_bf16 v[6:9], v[168:171], v[210:213], v[6:9]
	v_mfma_f32_16x16x32_bf16 v[2:5], v[176:179], v[210:213], v[2:5]
	v_mfma_f32_16x16x32_bf16 v[54:57], v[172:175], v[188:191], v[54:57]
	v_mfma_f32_16x16x32_bf16 v[50:53], v[180:183], v[188:191], v[50:53]
	v_mfma_f32_16x16x32_bf16 v[38:41], v[172:175], v[198:201], v[38:41]
	v_mfma_f32_16x16x32_bf16 v[34:37], v[180:183], v[198:201], v[34:37]
	v_mfma_f32_16x16x32_bf16 v[22:25], v[172:175], v[206:209], v[22:25]
	v_mfma_f32_16x16x32_bf16 v[18:21], v[180:183], v[206:209], v[18:21]
	v_mfma_f32_16x16x32_bf16 v[6:9], v[172:175], v[214:217], v[6:9]
	v_mfma_f32_16x16x32_bf16 v[2:5], v[180:183], v[214:217], v[2:5]
	s_setprio 0
	s_barrier
	s_add_i32 s67, s67, 2
	s_add_u32 s42, s42, 0x100
	s_addc_u32 s43, s43, 0
	s_add_u32 s65, s65, 0x100
	s_addc_u32 s66, s66, 0
	s_cmpk_gt_u32 s67, 0xfd
	s_cbranch_scc0 .LBB0_897
	s_and_b64 vcc, exec, s[14:15]
	s_cbranch_vccz .LBB0_900
	s_barrier
